# prep phase: copy items split 2 vs 4 per wave between workgroups with and without a compression item
# baseline (speedup 1.0000x reference)
; DI void phase_prep(const Args& a, int layer, LAS unsigned char* lds) {
;     ...
;         for (int it = gw; it < 6 * 4 * 256; it += NGW) {
;             const int which = it / 1024, bg = (it / 256) & 3, st = it & 255, b = bg >> 1, g = bg & 1;
;             if (which >= 3) {
;                 const int srccol = (which == 3 ? C_KS : which == 4 ? C_KW : C_KB) + g * 64;
;                 bf16_t* dst = (bf16_t*)(ws + (which == 3 ? WS_KSF : which == 4 ? WS_KWF : WS_KBF)) + (size_t)bg * 64 * S + (size_t)st * 4096;
;                 float rmax = 0.f;
; #pragma unroll
;                 for (int i = 0; i < 8; ++i) { const int tok = i * 8 + (lane >> 3), q = lane & 7;
;                     const u32x4 v = *(const u32x4*)(P + (size_t)(b * S + st * 64 + tok) * NP + srccol + q * 8);
.LBB0_340:
	s_and_b64 vcc, exec, s[0:1]
	s_cbranch_vccz .LBB0_406
	v_mov_b32_e32 v42, v185
	v_readlane_b32 s0, v252, 34
	v_ashrrev_i32_e32 v44, 6, v42
	v_and_b32_e32 v15, 31, v42
	v_add_u32_e32 v14, s0, v44
	s_movk_i32 s0, 0x17ff
	v_cmp_lt_i32_e32 vcc, s0, v14
	s_and_saveexec_b64 s[0:1], vcc
	s_xor_b64 s[0:1], exec, s[0:1]
	v_and_b32_e32 v128, 31, v42
	s_or_saveexec_b64 s[24:25], s[0:1]
	v_readlane_b32 s0, v252, 5
	v_readlane_b32 s1, v252, 6
	s_load_dword s19, s[0:1], 0x0
	v_and_b32_e32 v45, 63, v42
	v_lshlrev_b32_e32 v43, 5, v42
	s_waitcnt lgkmcnt(0)
	s_lshl_b32 s27, s19, 3
	s_xor_b64 exec, exec, s[24:25]
	s_cbranch_execz .LBB0_353
	s_movk_i32 s0, 0x2400
	v_lshrrev_b32_e32 v3, 3, v42
	v_mul_lo_u32 v0, v44, s0
	v_lshlrev_b32_e32 v1, 4, v42
	v_and_b32_e32 v18, 4, v3
	v_lshrrev_b32_e32 v3, 2, v42
	v_add_u32_e32 v16, 0, v0
	v_lshrrev_b32_e32 v17, 3, v45
	v_and_b32_e32 v128, 0x70, v1
	v_and_b32_e32 v20, 12, v3
	v_and_b32_e32 v3, 7, v42
	v_lshl_add_u64 v[4:5], s[30:31], 0, v[128:129]
	v_add_u32_e32 v2, v16, v128
	v_lshlrev_b32_e32 v128, 4, v3
	v_and_b32_e32 v3, 48, v1
	v_readlane_b32 s0, v255, 12
	v_or_b32_e32 v24, 24, v17
	s_waitcnt vmcnt(0)
	v_bitop3_b32 v37, v1, 48, 64 bitop3:0xe0
	s_lshl_b32 s8, s0, 4
	v_and_b32_e32 v9, 64, v1
	v_or_b32_e32 v1, v37, v17
	v_and_or_b32 v10, v24, 15, v3
	s_movk_i32 s0, 0x80
	v_and_b32_e32 v21, 0xe0, v43
	v_or_b32_e32 v28, 56, v17
	v_or_b32_e32 v39, 0x80, v1
	v_or3_b32 v41, v10, v9, s0
	v_bitop3_b32 v10, v17, 23, 48 bitop3:0xc8
	s_movk_i32 s0, 0x100
	v_or_b32_e32 v48, 0x180, v1
	v_bitop3_b32 v1, v17, 31, 56 bitop3:0xc8
	v_lshlrev_b32_e32 v0, 3, v45
	v_and_b32_e32 v19, 15, v42
	v_mul_u32_u24_e32 v8, 0x90, v17
	v_or_b32_e32 v23, 16, v17
	v_or3_b32 v47, v21, v10, s0
	v_or3_b32 v49, v21, v1, s0
	v_and_or_b32 v1, v28, 15, v3
	s_movk_i32 s0, 0x180
	v_lshl_add_u64 v[6:7], s[30:31], 0, v[128:129]
	v_cmp_eq_u32_e32 vcc, 0, v45
	s_add_i32 s8, s8, -12
	v_or_b32_e32 v22, 8, v17
	v_or_b32_e32 v25, 32, v17
	v_or_b32_e32 v26, 40, v17
	v_or_b32_e32 v27, 48, v17
	v_or_b32_e32 v29, 32, v15
	v_or_b32_e32 v30, 16, v19
	v_or_b32_e32 v31, 16, v18
	v_or_b32_e32 v32, 32, v19
	v_or_b32_e32 v33, 48, v19
	v_or_b32_e32 v34, 32, v18
	v_or_b32_e32 v35, 16, v20
	v_or_b32_e32 v36, 48, v18
	v_or_b32_e32 v38, v21, v23
	v_or_b32_e32 v40, v21, v24
	v_bitop3_b32 v46, v17, 15, 40 bitop3:0xc8
	v_or3_b32 v50, v1, v9, s0
	s_mov_b64 s[40:41], 0
	v_add_u32_e32 v51, v2, v8
	v_lshlrev_b32_e32 v8, 1, v0
	v_mov_b32_e32 v52, v14
	v_readlane_b32 s1, v255, 13
	v_readfirstlane_b32 s101, v14
	s_nop 1
	s_cmp_lt_u32 s101, 0x400
	s_movk_i32 s100, 0x13ff
	s_movk_i32 s101, 0x400
	s_cselect_b32 s100, 0x17ff, s100
	s_cselect_b32 s101, 0x1400, s101
	s_branch .LBB0_347

; DI void phase_prep(const Args& a, int layer, LAS unsigned char* lds) {
;     ...
;         for (int it = gw; it < 6 * 4 * 256; it += NGW) {
.LBB0_346:
	s_or_b64 exec, exec, s[42:43]
	v_add_u32_e32 v52, s101, v52
	s_mov_b32 s0, s100
	v_cmp_lt_i32_e64 s[0:1], s0, v52
	s_or_b64 s[40:41], s[0:1], s[40:41]
	s_andn2_b64 exec, exec, s[40:41]
	s_cbranch_execz .LBB0_352
